# G5 start skew 8 groups x s_sleep 32 (v75 otherwise)
# baseline (speedup 1.0000x reference)
.LBB0_1245:
	s_cmp_lt_i32 s31, 1
	s_cbranch_scc1 .LBB0_1272
	s_bfe_u32 s4, s2, 0x30003
	s_cmp_eq_u32 s4, 0
	s_cbranch_scc1 .Lskew_done_g5

.Lskew_done_g5:
	s_lshl_b32 s35, s88, 10
	v_lshlrev_b32_e32 v12, 4, v8
	v_add_u32_e32 v0, s35, v12
	v_add_u32_e32 v1, 0x2000, v0
	v_ashrrev_i32_e32 v2, 31, v1
	v_lshrrev_b32_e32 v2, 22, v2
	v_add_u32_e32 v2, v1, v2
	v_ashrrev_i32_e32 v9, 10, v2
	v_mul_i32_i24_e32 v2, 0x400, v9
	v_sub_u32_e32 v1, v1, v2
	v_lshrrev_b32_e32 v2, 4, v1
	v_bitop3_b32 v1, v2, v1, 32 bitop3:0x6c
	v_ashrrev_i32_e32 v2, 31, v1
	v_lshrrev_b32_e32 v2, 26, v2
	v_add_u32_e32 v2, v1, v2
	v_ashrrev_i32_e32 v10, 6, v2
	v_lshlrev_b32_e32 v3, 3, v9
	v_and_b32_e32 v2, 0xffc0, v2
	v_and_b32_e32 v3, -16, v3
	v_sub_u32_e32 v1, v1, v2
	v_add_u32_e32 v3, v10, v3
	v_lshrrev_b16_e32 v2, 7, v1
	v_and_b32_e32 v4, 3, v10
	s_mov_b32 s4, 0x1fffe0
	v_lshrrev_b32_e32 v5, 2, v3
	v_lshlrev_b32_e32 v6, 1, v3
	v_and_b32_e32 v2, 1, v2
	v_and_or_b32 v4, v3, s4, v4
	v_and_b32_e32 v5, 4, v5
	v_and_b32_e32 v6, 24, v6
	v_add_u16_e32 v1, v1, v2
	v_mov_b32_e32 v2, 1
	v_or3_b32 v4, v4, v5, v6
	v_lshlrev_b32_e32 v5, 5, v9
	v_ashrrev_i16_sdwa v1, v2, sext(v1) dst_sel:DWORD dst_unused:UNUSED_PAD src0_sel:DWORD src1_sel:BYTE_0
	v_and_b32_e32 v5, 32, v5
	v_bfe_i32 v11, v1, 0, 16
	v_add_lshl_u32 v1, v5, v11, 1
	v_lshl_add_u32 v168, v4, 11, v1
	v_lshl_add_u32 v170, v3, 11, v1
	v_ashrrev_i32_e32 v1, 31, v0
	v_lshrrev_b32_e32 v1, 22, v1
	v_add_u32_e32 v1, v0, v1
	v_ashrrev_i32_e32 v13, 10, v1
	v_mul_i32_i24_e32 v1, 0x400, v13
	v_sub_u32_e32 v0, v0, v1
	v_lshrrev_b32_e32 v1, 4, v0
	v_bitop3_b32 v0, v1, v0, 32 bitop3:0x6c
	v_ashrrev_i32_e32 v1, 31, v0
	v_lshrrev_b32_e32 v1, 26, v1
	v_add_u32_e32 v1, v0, v1
	v_lshlrev_b32_e32 v3, 3, v13
	v_ashrrev_i32_e32 v14, 6, v1
	v_and_b32_e32 v3, -16, v3
	s_lshr_b32 s20, s33, 8
	v_add_u32_e32 v3, v14, v3
	s_add_u32 s44, s40, 0x1600000
	v_and_b32_e32 v4, 3, v14
	v_lshrrev_b32_e32 v5, 2, v3
	v_lshlrev_b32_e32 v6, 1, v3
	v_and_b32_e32 v1, 0xc0, v1
	s_addc_u32 s45, s41, 0
	v_and_or_b32 v4, v3, s4, v4
	v_and_b32_e32 v5, 4, v5
	v_and_b32_e32 v6, 24, v6
	v_sub_u32_e32 v0, v0, v1
	s_add_i32 s4, 0, 0x20200
	v_or3_b32 v4, v4, v5, v6
	v_ashrrev_i16_sdwa v6, v2, sext(v0) dst_sel:DWORD dst_unused:UNUSED_PAD src0_sel:DWORD src1_sel:BYTE_0
	v_mov_b32_e32 v0, s4
	ds_read_b96 v[0:2], v0
	v_lshlrev_b32_e32 v5, 5, v13
	v_and_b32_e32 v5, 32, v5
	v_bfe_i32 v15, v6, 0, 16
	v_add_lshl_u32 v5, v5, v15, 1
	s_waitcnt lgkmcnt(0)
	v_readfirstlane_b32 s54, v0
	v_readfirstlane_b32 s4, v1
	s_ashr_i32 s55, s54, 31
	s_ashr_i32 s5, s4, 31
	v_readfirstlane_b32 s16, v2
	s_lshl_b64 s[12:13], s[54:55], 19
	s_lshl_b64 s[14:15], s[4:5], 19
	s_cmp_eq_u32 s16, 0
	s_cselect_b32 s16, s44, 0
	s_cselect_b32 s5, s45, 0
	s_cselect_b32 s17, s49, 0
	s_cselect_b32 s21, s48, 0
	s_add_u32 s58, s16, s14
	s_addc_u32 s59, s5, s15
	s_add_i32 s46, s35, 0
	v_lshl_add_u32 v172, v4, 11, v5
	s_add_i32 m0, s46, 0x10000
	v_lshl_add_u32 v174, v3, 11, v5
	global_load_lds_dwordx4 v172, s[58:59]
	s_add_i32 m0, s46, 0x12000
	s_add_u32 s14, s58, 0x40000
	global_load_lds_dwordx4 v168, s[58:59]
	s_addc_u32 s15, s59, 0
	s_add_i32 m0, s46, 0x14000
	v_mov_b32_e32 v177, 0
	global_load_lds_dwordx4 v172, s[14:15]
	s_add_i32 m0, s46, 0x16000
	s_add_u32 s56, s21, s12
	s_addc_u32 s57, s17, s13
	s_add_i32 s47, s46, 0x2000
	global_load_lds_dwordx4 v168, s[14:15]
	s_mov_b32 m0, s46
	s_add_u32 s12, s56, 0x40000
	global_load_lds_dwordx4 v174, s[56:57]
	s_mov_b32 m0, s47
	s_addc_u32 s13, s57, 0
	s_add_i32 s62, s46, 0x4000
	global_load_lds_dwordx4 v170, s[56:57]
	s_mov_b32 m0, s62
	s_add_i32 s63, s46, 0x6000
	global_load_lds_dwordx4 v174, s[12:13]
	s_mov_b32 m0, s63
	v_mov_b32_e32 v173, v177
	global_load_lds_dwordx4 v170, s[12:13]
	v_mov_b32_e32 v169, v177
	v_mov_b32_e32 v175, v177
	v_mov_b32_e32 v171, v177
	s_cmp_eq_u32 s20, 1
	s_mov_b32 s65, 0
	v_lshl_add_u64 v[6:7], s[58:59], 0, v[172:173]
	v_lshl_add_u64 v[4:5], s[58:59], 0, v[168:169]
	v_lshl_add_u64 v[0:1], s[56:57], 0, v[174:175]
	s_cselect_b64 s[12:13], -1, 0
	s_cmp_lg_u32 s20, 1
	v_lshl_add_u64 v[2:3], s[56:57], 0, v[170:171]
	s_cbranch_scc1 .LBB0_1248
	s_barrier
